# v9 + P7 LN1 row loop: next row's loads in flight while the current row is normalised
# speedup vs baseline: 1.0027x; 1.0027x over previous
; template <unsigned MASK> __global__ void __launch_bounds__(NTHREADS, 2) fwd(Args A0) {
;     ...
;             PHASE_FRAME; const int cwb = CW_ITEM + 64 * 8 * l + 1024 * rep; (void)cwb;
;             const bf16_t* PRE = (const bf16_t*)(ws + WS_PRE1); bf16_t* XB = (bf16_t*)(ws + WS_XB);
;             const Args A = load_args();
;             const float* g1 = A.in[I_LN1G] + l * D; const float* b1 = A.in[I_LN1B] + l * D; const int lane = F.lane;
;             f32x4 g1v[8], b1v[8];
; #pragma unroll
;             for (int j = 0; j < 4; ++j) { const int cix = 512 * j + 8 * lane; g1v[2 * j] = *(const f32x4*)(g1 + cix); g1v[2 * j + 1] = *(const f32x4*)(g1 + cix + 4); b1v[2 * j] = *(const f32x4*)(b1 + cix); b1v[2 * j + 1] = *(const f32x4*)(b1 + cix + 4); }
;             for (int r = F.bid * NWAVES + F.wave; r < M; r += F.G * NWAVES) {
;                 f32x4 v[8]; float s = 0.f;
;                 u32x4 pw[4];
; #pragma unroll
;                 for (int j = 0; j < 4; ++j) pw[j] = *(const u32x4*)(PRE + (size_t)r * D + 512 * j + 8 * lane);
;                 asm volatile("" : "+v"(pw[0]), "+v"(pw[1]), "+v"(pw[2]), "+v"(pw[3]));
.LBB0_1947:
	s_or_b64 exec, exec, s[0:1]
	v_readlane_b32 s0, v254, 1
	v_readlane_b32 s8, v254, 0
	v_readlane_b32 s6, v254, 9
	v_readlane_b32 s1, v254, 2
	v_readlane_b32 s7, v254, 3
	s_waitcnt lgkmcnt(0)
	s_barrier
	v_readlane_b32 s4, v254, 21
	s_lshl_b32 s9, s8, 3
	v_readlane_b32 s5, v254, 22
	s_add_i32 s8, s9, s6
	s_mov_b32 s10, s4
	s_mov_b64 s[4:5], s[96:97]
	s_cmpk_gt_i32 s8, 0x27ff
	v_mbcnt_lo_u32_b32 v0, -1, 0
	v_mbcnt_hi_u32_b32 v0, -1, v0
	s_cbranch_scc1 .LBB0_1950
	s_load_dwordx4 s[12:15], s[4:5], 0xc8
	s_lshl_b32 s4, s10, 11
	s_ashr_i32 s5, s4, 31
	s_lshl_b64 s[4:5], s[4:5], 2
	v_lshlrev_b32_e32 v64, 3, v0
	s_waitcnt lgkmcnt(0)
	s_add_u32 s10, s12, s4
	s_addc_u32 s11, s13, s5
	s_add_u32 s4, s14, s4
	v_ashrrev_i32_e32 v65, 31, v64
	s_addc_u32 s5, s15, s5
	v_lshlrev_b64 v[8:9], 2, v[64:65]
	v_lshl_add_u64 v[48:49], s[10:11], 0, v[8:9]
	v_lshl_add_u64 v[56:57], s[4:5], 0, v[8:9]
	s_movk_i32 s4, 0x1000
	global_load_dwordx4 v[0:3], v[48:49], off offset:16
	global_load_dwordx4 v[4:7], v[48:49], off
	global_load_dwordx4 v[8:11], v[56:57], off offset:16
	global_load_dwordx4 v[12:15], v[56:57], off
	global_load_dwordx4 v[16:19], v[48:49], off offset:2064
	global_load_dwordx4 v[20:23], v[48:49], off offset:2048
	global_load_dwordx4 v[24:27], v[56:57], off offset:2064
	global_load_dwordx4 v[28:31], v[56:57], off offset:2048
	v_add_co_u32_e32 v50, vcc, s4, v48
	s_mov_b64 s[10:11], 0x1000
	s_nop 0
	v_addc_co_u32_e32 v51, vcc, 0, v49, vcc
	v_add_co_u32_e32 v58, vcc, s4, v56
	s_mov_b64 s[4:5], 0x1800
	v_lshl_add_u64 v[36:37], v[48:49], 0, s[10:11]
	v_lshl_add_u64 v[44:45], v[56:57], 0, s[10:11]
	v_addc_co_u32_e32 v59, vcc, 0, v57, vcc
	v_lshl_add_u64 v[52:53], v[48:49], 0, s[4:5]
	v_lshl_add_u64 v[60:61], v[56:57], 0, s[4:5]
	global_load_dwordx4 v[32:35], v[50:51], off
	s_nop 0
	global_load_dwordx4 v[36:39], v[36:37], off offset:16
	s_nop 0
	global_load_dwordx4 v[40:43], v[58:59], off
	s_nop 0
	global_load_dwordx4 v[44:47], v[44:45], off offset:16
	s_nop 0
	global_load_dwordx4 v[48:51], v[50:51], off offset:2048
	s_nop 0
	global_load_dwordx4 v[52:55], v[52:53], off offset:16
	s_nop 0
	global_load_dwordx4 v[56:59], v[58:59], off offset:2048
	s_nop 0
	global_load_dwordx4 v[60:63], v[60:61], off offset:16
	s_lshl_b32 s4, s7, 3
	s_ashr_i32 s5, s6, 31
	s_ashr_i32 s7, s9, 31
	s_add_u32 s6, s6, s9
	s_addc_u32 s7, s5, s7
	s_lshl_b64 s[6:7], s[6:7], 12
	s_add_u32 s0, s0, s6
	s_addc_u32 s1, s1, s7
	v_lshl_add_u64 v[64:65], v[64:65], 1, s[0:1]
	s_mov_b64 s[0:1], 0x3fbd0c00
	s_ashr_i32 s5, s4, 31
	v_lshl_add_u64 v[64:65], v[64:65], 0, s[0:1]
	s_lshl_b64 s[6:7], s[4:5], 12
	global_load_dwordx4 v[120:123], v[64:65], off offset:-3072
	global_load_dwordx4 v[124:127], v[64:65], off offset:-2048
	global_load_dwordx4 v[128:131], v[64:65], off offset:-1024
	global_load_dwordx4 v[132:135], v[64:65], off
	s_waitcnt vmcnt(0)
	s_branch .Lp7_body

; __device__ __forceinline__ float bflo(unsigned w) { return __uint_as_float(w << 16); }
; __device__ __forceinline__ float bfhi(unsigned w) { return __uint_as_float(w & 0xffff0000u); }
; template <unsigned MASK> __global__ void __launch_bounds__(NTHREADS, 2) fwd(Args A0) {
;     ...
;             for (int r = F.bid * NWAVES + F.wave; r < M; r += F.G * NWAVES) {
;                 f32x4 v[8]; float s = 0.f;
;                 u32x4 pw[4];
; #pragma unroll
;                 for (int j = 0; j < 4; ++j) pw[j] = *(const u32x4*)(PRE + (size_t)r * D + 512 * j + 8 * lane);
;                 asm volatile("" : "+v"(pw[0]), "+v"(pw[1]), "+v"(pw[2]), "+v"(pw[3]));
; #pragma unroll
;                 for (int j = 0; j < 4; ++j) { const u32x4 w = pw[j];
;                     v[2 * j] = (f32x4){bflo(w.x), bfhi(w.x), bflo(w.y), bfhi(w.y)}; v[2 * j + 1] = (f32x4){bflo(w.z), bfhi(w.z), bflo(w.w), bfhi(w.w)};
;                     s += ((v[2 * j][0] + v[2 * j][1]) + (v[2 * j][2] + v[2 * j][3])) + ((v[2 * j + 1][0] + v[2 * j + 1][1]) + (v[2 * j + 1][2] + v[2 * j + 1][3])); }
;                 const float mean = wave_sum(s) * (1.0f / D); float q = 0.f;
; #pragma unroll
;                 for (int j = 0; j < 8; ++j) { v[j] = v[j] - mean; q += (v[j][0] * v[j][0] + v[j][1] * v[j][1]) + (v[j][2] * v[j][2] + v[j][3] * v[j][3]); }
.Lp7_body:
	v_mov_b32_e32 v92, v201
	s_add_i32 s8, s8, s4
	s_cmpk_lt_i32 s8, 0x2800
	v_mov_b64_e32 v[66:67], v[120:121]
	v_mov_b64_e32 v[68:69], v[122:123]
	v_mov_b64_e32 v[70:71], v[124:125]
	v_mov_b64_e32 v[72:73], v[126:127]
	v_mov_b64_e32 v[82:83], v[128:129]
	v_mov_b64_e32 v[84:85], v[130:131]
	v_mov_b64_e32 v[104:105], v[132:133]
	v_mov_b64_e32 v[106:107], v[134:135]
	s_cbranch_scc0 .Lp7_nopf
	v_lshl_add_u64 v[136:137], v[64:65], 0, s[6:7]
	global_load_dwordx4 v[120:123], v[136:137], off offset:-3072
	global_load_dwordx4 v[124:127], v[136:137], off offset:-2048
	global_load_dwordx4 v[128:131], v[136:137], off offset:-1024
	global_load_dwordx4 v[132:135], v[136:137], off
.Lp7_nopf:
	s_nop 0
	v_lshlrev_b32_e32 v99, 16, v68
	v_lshlrev_b32_e32 v98, 16, v66
	v_and_b32_e32 v103, 0xffff0000, v68
	v_and_b32_e32 v102, 0xffff0000, v66
	v_lshlrev_b32_e32 v91, 16, v69
	v_lshlrev_b32_e32 v90, 16, v67
	v_and_b32_e32 v101, 0xffff0000, v69
	v_and_b32_e32 v100, 0xffff0000, v67
	v_pk_add_f32 v[66:67], v[98:99], v[102:103]
	v_pk_add_f32 v[68:69], v[90:91], v[100:101]
	v_lshlrev_b32_e32 v87, 16, v71
	v_lshlrev_b32_e32 v86, 16, v70
	v_and_b32_e32 v95, 0xffff0000, v71
	v_and_b32_e32 v94, 0xffff0000, v70
	v_lshlrev_b32_e32 v89, 16, v73
	v_lshlrev_b32_e32 v88, 16, v72
	v_and_b32_e32 v97, 0xffff0000, v73
	v_and_b32_e32 v96, 0xffff0000, v72
	v_pk_add_f32 v[108:109], v[66:67], v[68:69]
	v_pk_add_f32 v[110:111], v[86:87], v[94:95]
	v_pk_add_f32 v[112:113], v[88:89], v[96:97]
	v_lshlrev_b32_e32 v74, 16, v104
	v_and_b32_e32 v93, 0xffff0000, v104
	v_lshlrev_b32_e32 v78, 16, v105
	v_and_b32_e32 v79, 0xffff0000, v105
	v_lshlrev_b32_e32 v73, 16, v106
	v_and_b32_e32 v69, 0xffff0000, v106
	v_lshlrev_b32_e32 v71, 16, v107
	v_and_b32_e32 v67, 0xffff0000, v107
	v_pk_add_f32 v[104:105], v[108:109], v[108:109] op_sel:[0,1] op_sel_hi:[1,0]
	v_pk_add_f32 v[106:107], v[110:111], v[110:111] op_sel:[0,1] op_sel_hi:[1,0]
	v_pk_add_f32 v[108:109], v[112:113], v[112:113] op_sel:[0,1] op_sel_hi:[1,0]
	v_lshlrev_b32_e32 v76, 16, v82
	v_and_b32_e32 v77, 0xffff0000, v82
	v_lshlrev_b32_e32 v82, 16, v83
	v_and_b32_e32 v83, 0xffff0000, v83
	v_lshlrev_b32_e32 v80, 16, v84
	v_and_b32_e32 v81, 0xffff0000, v84
	v_lshlrev_b32_e32 v84, 16, v85
	v_and_b32_e32 v85, 0xffff0000, v85
	v_mov_b32_e32 v105, v74
	v_mov_b32_e32 v107, v78
	v_mov_b32_e32 v109, v79
	v_add_f32_e32 v72, v76, v77
	v_add_f32_e32 v68, v82, v83
	v_add_f32_e32 v70, v80, v81
	v_add_f32_e32 v66, v84, v85
	v_pk_add_f32 v[104:105], v[104:105], v[92:93]
	v_pk_add_f32 v[106:107], v[106:107], v[108:109]
	v_pk_add_f32 v[108:109], v[70:71], v[66:67]
	v_pk_add_f32 v[104:105], v[104:105], v[106:107]
	v_pk_add_f32 v[106:107], v[72:73], v[68:69]
	v_mbcnt_lo_u32_b32 v68, -1, 0
	v_mbcnt_hi_u32_b32 v68, -1, v68
	s_nop 0
	v_pk_add_f32 v[106:107], v[106:107], v[108:109]
	v_lshlrev_b32_e32 v68, 2, v68
	v_pk_add_f32 v[104:105], v[104:105], v[106:107]
	v_xor_b32_e32 v70, 4, v68
	v_add_f32_e32 v66, v104, v105
	ds_bpermute_b32 v70, v70, v66
	s_waitcnt lgkmcnt(0)
	v_add_f32_e32 v66, v66, v70
	v_xor_b32_e32 v70, 8, v68
	ds_bpermute_b32 v70, v70, v66
	s_waitcnt lgkmcnt(0)
	v_add_f32_e32 v66, v66, v70
	v_xor_b32_e32 v70, 16, v68
	ds_bpermute_b32 v70, v70, v66
	s_waitcnt lgkmcnt(0)
	v_add_f32_e32 v66, v66, v70
	v_xor_b32_e32 v70, 32, v68
	ds_bpermute_b32 v70, v70, v66
	s_waitcnt lgkmcnt(0)
	v_add_f32_e32 v66, v66, v70
	v_xor_b32_e32 v70, 64, v68
	ds_bpermute_b32 v70, v70, v66
	v_xor_b32_e32 v68, 0x80, v68
	s_waitcnt lgkmcnt(0)
	v_add_f32_e32 v66, v66, v70
	ds_bpermute_b32 v68, v68, v66
	s_waitcnt lgkmcnt(0)
	v_add_f32_e32 v68, v66, v68
	v_fmac_f32_e32 v102, 0xba000000, v68
	v_fmac_f32_e32 v103, 0xba000000, v68
	v_fmac_f32_e32 v100, 0xba000000, v68
	v_fmac_f32_e32 v98, 0xba000000, v68
	v_fmac_f32_e32 v101, 0xba000000, v68
	v_fmac_f32_e32 v99, 0xba000000, v68
	v_mov_b32_e32 v105, v103
	v_mov_b32_e32 v107, v102
	v_pk_mul_f32 v[102:103], v[102:103], v[102:103]
	v_fmac_f32_e32 v90, 0xba000000, v68
	v_fmac_f32_e32 v91, 0xba000000, v68
	v_mov_b32_e32 v104, v99
	v_mov_b32_e32 v106, v98
	v_pk_fma_f32 v[98:99], v[98:99], v[98:99], v[102:103]
	v_mov_b32_e32 v103, v101
	v_mov_b32_e32 v109, v100
	v_pk_mul_f32 v[100:101], v[100:101], v[100:101]
	v_mov_b32_e32 v102, v91
	v_mov_b32_e32 v108, v90
	v_pk_fma_f32 v[90:91], v[90:91], v[90:91], v[100:101]
	v_fmac_f32_e32 v94, 0xba000000, v68
	v_fmac_f32_e32 v95, 0xba000000, v68
	v_fmac_f32_e32 v87, 0xba000000, v68
	v_pk_add_f32 v[98:99], v[98:99], v[90:91]
	v_fmac_f32_e32 v86, 0xba000000, v68
	v_mov_b32_e32 v90, v87
	v_mov_b32_e32 v91, v95
	v_mov_b32_e32 v87, v94
	v_pk_mul_f32 v[100:101], v[90:91], v[90:91]
	v_pk_mul_f32 v[94:95], v[86:87], v[86:87]
	v_fmac_f32_e32 v77, 0xba000000, v68
	v_pk_mov_b32 v[110:111], v[94:95], v[100:101] op_sel:[1,0]
	v_mov_b32_e32 v95, v101
	v_pk_add_f32 v[100:101], v[110:111], v[94:95]
	v_fmac_f32_e32 v76, 0xba000000, v68
	v_fmac_f32_e32 v96, 0xba000000, v68
	v_fmac_f32_e32 v89, 0xba000000, v68
	v_mul_f32_e32 v66, v76, v76
	v_mul_f32_e32 v70, v77, v77
	v_pk_add_f32 v[98:99], v[98:99], v[98:99] op_sel:[0,1] op_sel_hi:[1,0]
	v_pk_add_f32 v[100:101], v[100:101], v[100:101] op_sel:[0,1] op_sel_hi:[1,0]
	v_fmac_f32_e32 v88, 0xba000000, v68
	v_fmac_f32_e32 v97, 0xba000000, v68
	v_mov_b32_e32 v94, v89
	v_mov_b32_e32 v89, v96
	v_mov_b32_e32 v99, v66
	v_mov_b32_e32 v101, v70
	v_mul_f32_e32 v66, v96, v96
	v_mov_b32_e32 v95, v97
	v_fmac_f32_e32 v83, 0xba000000, v68
	v_fmac_f32_e32 v82, 0xba000000, v68
	v_pk_add_f32 v[98:99], v[98:99], v[100:101]
	v_pk_fma_f32 v[100:101], v[88:89], v[88:89], v[66:67] op_sel_hi:[1,1,0]
	v_mul_f32_e32 v66, v97, v97
	v_mul_f32_e32 v72, v82, v82
	v_mul_f32_e32 v75, v83, v83
; __device__ __forceinline__ unsigned pk2(float lo, float hi) { typedef float f2_ __attribute__((ext_vector_type(2))); const bf16x2n_t b = __builtin_convertvector((f2_){lo, hi}, bf16x2n_t); return __builtin_bit_cast(unsigned, b); }
; template <unsigned MASK> __global__ void __launch_bounds__(NTHREADS, 2) fwd(Args A0) {
;     ...
;                 const float mean = wave_sum(s) * (1.0f / D); float q = 0.f;
; #pragma unroll
;                 for (int j = 0; j < 8; ++j) { v[j] = v[j] - mean; q += (v[j][0] * v[j][0] + v[j][1] * v[j][1]) + (v[j][2] * v[j][2] + v[j][3] * v[j][3]); }
;                 const float rstd = 1.0f / sqrtf(wave_sum(q) * (1.0f / D) + LN_EPS);
; #pragma unroll
;                 for (int j = 0; j < 4; ++j) { const int cix = 512 * j + 8 * lane;
;                     const f32x4 y0 = v[2 * j] * rstd * g1v[2 * j] + b1v[2 * j], y1 = v[2 * j + 1] * rstd * g1v[2 * j + 1] + b1v[2 * j + 1];
;                     *(u32x4*)(XB + (size_t)r * D + cix) = (u32x4){pk2(y0[0], y0[1]), pk2(y0[2], y0[3]), pk2(y1[0], y1[1]), pk2(y1[2], y1[3])}; }
;             }
	v_pk_fma_f32 v[96:97], v[94:95], v[94:95], v[66:67] op_sel_hi:[1,1,0]
	v_mov_b32_e32 v101, v72
	v_mov_b32_e32 v97, v75
	v_pk_add_f32 v[96:97], v[100:101], v[96:97]
	v_fmac_f32_e32 v81, 0xba000000, v68
	v_fmac_f32_e32 v80, 0xba000000, v68
	v_fmac_f32_e32 v85, 0xba000000, v68
	v_fmac_f32_e32 v84, 0xba000000, v68
	v_pk_add_f32 v[96:97], v[98:99], v[96:97]
	v_pk_mul_f32 v[98:99], v[84:85], v[84:85]
	v_pk_mul_f32 v[100:101], v[80:81], v[80:81]
	v_fmac_f32_e32 v73, 0xba000000, v68
	v_pk_mov_b32 v[110:111], v[100:101], v[98:99] op_sel:[1,0]
	v_mov_b32_e32 v101, v99
	v_pk_add_f32 v[98:99], v[110:111], v[100:101]
	v_fmac_f32_e32 v93, 0xba000000, v68
	v_fmac_f32_e32 v69, 0xba000000, v68
	v_mul_f32_e32 v66, v73, v73
	v_pk_add_f32 v[96:97], v[96:97], v[96:97] op_sel:[0,1] op_sel_hi:[1,0]
	v_fmac_f32_e32 v74, 0xba000000, v68
	v_fmac_f32_e32 v79, 0xba000000, v68
	v_fmac_f32_e32 v78, 0xba000000, v68
	v_mov_b32_e32 v75, v93
	v_fmac_f32_e32 v67, 0xba000000, v68
	v_fmac_f32_e32 v71, 0xba000000, v68
	v_mul_f32_e32 v68, v69, v69
	v_mov_b32_e32 v97, v66
	v_pk_add_f32 v[98:99], v[98:99], v[98:99] op_sel:[0,1] op_sel_hi:[1,0]
	v_mul_f32_e32 v66, v93, v93
	v_mov_b32_e32 v99, v68
	v_pk_fma_f32 v[92:93], v[74:75], v[74:75], v[66:67] op_sel_hi:[1,1,0]
	v_mul_f32_e32 v66, v79, v79
	v_mul_f32_e32 v70, v71, v71
	v_mul_f32_e32 v72, v67, v67
	v_pk_add_f32 v[96:97], v[96:97], v[98:99]
	v_pk_fma_f32 v[98:99], v[78:79], v[78:79], v[66:67] op_sel_hi:[1,1,0]
	v_mov_b32_e32 v93, v70
	v_mov_b32_e32 v99, v72
	v_pk_add_f32 v[92:93], v[92:93], v[98:99]
	v_mbcnt_lo_u32_b32 v68, -1, 0
	v_mbcnt_hi_u32_b32 v68, -1, v68
	s_nop 0
	v_pk_add_f32 v[92:93], v[96:97], v[92:93]
	v_lshlrev_b32_e32 v68, 2, v68
	v_add_f32_e32 v66, v92, v93
	v_xor_b32_e32 v70, 4, v68
	ds_bpermute_b32 v70, v70, v66
	s_waitcnt lgkmcnt(0)
	v_add_f32_e32 v66, v66, v70
	v_xor_b32_e32 v70, 8, v68
	ds_bpermute_b32 v70, v70, v66
	s_waitcnt lgkmcnt(0)
	v_add_f32_e32 v66, v66, v70
	v_xor_b32_e32 v70, 16, v68
	ds_bpermute_b32 v70, v70, v66
	s_waitcnt lgkmcnt(0)
	v_add_f32_e32 v66, v66, v70
	v_xor_b32_e32 v70, 32, v68
	ds_bpermute_b32 v70, v70, v66
	s_waitcnt lgkmcnt(0)
	v_add_f32_e32 v66, v66, v70
	v_xor_b32_e32 v70, 64, v68
	ds_bpermute_b32 v70, v70, v66
	v_xor_b32_e32 v68, 0x80, v68
	s_waitcnt lgkmcnt(0)
	v_add_f32_e32 v66, v66, v70
	ds_bpermute_b32 v68, v68, v66
	s_waitcnt lgkmcnt(0)
	v_add_f32_e32 v66, v66, v68
	v_fmamk_f32 v66, v66, 0x3a000000, v232
	v_cmp_gt_f32_e32 vcc, s89, v66
	v_mul_f32_e32 v68, 0x4f800000, v66
	s_nop 0
	v_cndmask_b32_e32 v66, v66, v68, vcc
	v_sqrt_f32_e32 v68, v66
	s_nop 0
	v_add_u32_e32 v70, -1, v68
	v_fma_f32 v72, -v70, v68, v66
	v_cmp_ge_f32_e64 s[0:1], 0, v72
	v_add_u32_e32 v72, 1, v68
	s_nop 0
	v_cndmask_b32_e64 v70, v68, v70, s[0:1]
	v_fma_f32 v68, -v72, v68, v66
	v_cmp_lt_f32_e64 s[0:1], 0, v68
	s_nop 1
	v_cndmask_b32_e64 v68, v70, v72, s[0:1]
	v_mul_f32_e32 v70, 0x37800000, v68
	v_cndmask_b32_e32 v68, v68, v70, vcc
	v_cmp_class_f32_e32 vcc, v66, v223
	s_nop 1
	v_cndmask_b32_e32 v66, v68, v66, vcc
	v_div_scale_f32 v68, s[0:1], v66, v66, 1.0
	v_rcp_f32_e32 v70, v68
	s_mov_b32 s0, 0xdc270000
	v_fma_f32 v72, -v68, v70, 1.0
	v_fmac_f32_e32 v70, v72, v70
	v_div_scale_f32 v72, vcc, 1.0, v66, 1.0
	v_mul_f32_e32 v92, v72, v70
	v_fma_f32 v93, -v68, v92, v72
	v_fmac_f32_e32 v92, v93, v70
	v_fma_f32 v68, -v68, v92, v72
	v_div_fmas_f32 v68, v68, v70, v92
	v_div_fixup_f32 v70, v68, v66, 1.0
	v_pk_mul_f32 v[92:93], v[70:71], v[106:107] op_sel_hi:[0,1]
	v_pk_mul_f32 v[96:97], v[70:71], v[108:109] op_sel_hi:[0,1]
	v_pk_fma_f32 v[98:99], v[96:97], v[6:7], v[14:15]
	v_pk_fma_f32 v[92:93], v[92:93], v[4:5], v[12:13]
	v_pk_mul_f32 v[96:97], v[70:71], v[104:105] op_sel_hi:[0,1]
	v_pk_mul_f32 v[86:87], v[70:71], v[86:87] op_sel_hi:[0,1]
	v_pk_mul_f32 v[90:91], v[70:71], v[90:91] op_sel_hi:[0,1]
	v_pk_mul_f32 v[88:89], v[70:71], v[88:89] op_sel_hi:[0,1]
	v_pk_mul_f32 v[94:95], v[70:71], v[94:95] op_sel_hi:[0,1]
	v_pk_mul_f32 v[100:101], v[70:71], v[102:103] op_sel_hi:[0,1]
	v_pk_fma_f32 v[102:103], v[96:97], v[0:1], v[8:9]
	v_cvt_pk_bf16_f32 v96, v92, v93
	v_add_co_u32_e32 v92, vcc, s0, v64
	v_pk_fma_f32 v[90:91], v[90:91], v[22:23], v[30:31]
	v_pk_fma_f32 v[86:87], v[86:87], v[20:21], v[28:29]
	v_pk_fma_f32 v[94:95], v[94:95], v[18:19], v[26:27]
	v_pk_fma_f32 v[88:89], v[88:89], v[16:17], v[24:25]
	v_pk_mul_f32 v[76:77], v[70:71], v[76:77] op_sel_hi:[0,1]
	v_addc_co_u32_e32 v93, vcc, -1, v65, vcc
	v_cvt_pk_bf16_f32 v86, v86, v87
	v_cvt_pk_bf16_f32 v87, v90, v91
	v_cvt_pk_bf16_f32 v88, v88, v89
	v_cvt_pk_bf16_f32 v89, v94, v95
	v_pk_fma_f32 v[76:77], v[76:77], v[32:33], v[40:41]
	v_pk_mul_f32 v[80:81], v[70:71], v[80:81] op_sel_hi:[0,1]
	v_mov_b32_e32 v68, v73
	v_mov_b32_e32 v66, v71
	global_store_dwordx4 v[92:93], v[86:89], off offset:-2048
	v_pk_mul_f32 v[82:83], v[70:71], v[82:83] op_sel_hi:[0,1]
	v_pk_mul_f32 v[84:85], v[70:71], v[84:85] op_sel_hi:[0,1]
	v_pk_fma_f32 v[86:87], v[80:81], v[36:37], v[44:45]
	v_cvt_pk_bf16_f32 v80, v76, v77
	v_pk_mul_f32 v[74:75], v[70:71], v[74:75] op_sel_hi:[0,1]
	v_pk_mul_f32 v[76:77], v[70:71], v[78:79] op_sel_hi:[0,1]
	v_pk_mul_f32 v[68:69], v[70:71], v[68:69] op_sel_hi:[0,1]
	v_pk_mul_f32 v[66:67], v[70:71], v[66:67] op_sel_hi:[0,1]
	v_pk_fma_f32 v[100:101], v[100:101], v[2:3], v[10:11]
	v_pk_fma_f32 v[82:83], v[82:83], v[34:35], v[42:43]
	v_pk_fma_f32 v[84:85], v[84:85], v[38:39], v[46:47]
	v_pk_fma_f32 v[76:77], v[76:77], v[50:51], v[58:59]
	v_pk_fma_f32 v[74:75], v[74:75], v[48:49], v[56:57]
	v_pk_fma_f32 v[70:71], v[66:67], v[54:55], v[62:63]
	v_pk_fma_f32 v[68:69], v[68:69], v[52:53], v[60:61]
	v_cvt_pk_bf16_f32 v97, v98, v99
	v_cvt_pk_bf16_f32 v98, v102, v103
	v_cvt_pk_bf16_f32 v99, v100, v101
	v_cvt_pk_bf16_f32 v81, v82, v83
	v_cvt_pk_bf16_f32 v82, v86, v87
	v_cvt_pk_bf16_f32 v83, v84, v85
	v_cvt_pk_bf16_f32 v66, v74, v75
	v_cvt_pk_bf16_f32 v67, v76, v77
	v_cvt_pk_bf16_f32 v68, v68, v69
	v_cvt_pk_bf16_f32 v69, v70, v71
	v_lshl_add_u64 v[64:65], v[64:65], 0, s[6:7]
	global_store_dwordx4 v[92:93], v[96:99], off offset:-3072
	global_store_dwordx4 v[92:93], v[80:83], off offset:-1024
	global_store_dwordx4 v[92:93], v[66:69], off
	s_cbranch_scc1 .LBB0_1949
